# P6 out-proj epilogue: residual x loads issued two row groups ahead into dead fragment registers, one counted wait per row group (was a 16-step load-wait-add ladder)
# baseline (speedup 1.0000x reference)
;     __device__ __forceinline__ void operator()(const f32x4 (&acc)[2][2][4][2], const Unit& u, int wr, int wc, int fr, int fq) const {
;         const int row0 = u.pm * 256 + wr * 64 + fr, col0 = u.pn * 256 + wc * 32 + 8 * fq;
; #pragma unroll
;         for (int ai = 0; ai < 2; ++ai)
; #pragma unroll
;             for (int m = 0; m < 4; ++m) {
;                 const int row = row0 + ai * 128 + m * 16; float s_ = 0.f;
; #pragma unroll
;                 for (int bj = 0; bj < 2; ++bj) {
;                     const size_t off = (size_t)row * 1024 + col0 + bj * 128;
;                     const f32x4 v0 = *(const f32x4*)(base + off) + acc[ai][bj][m][0], v1 = *(const f32x4*)(base + off + 4) + acc[ai][bj][m][1];
;                     s_ += ((v0[0] * v0[0] + v0[1] * v0[1]) + (v0[2] * v0[2] + v0[3] * v0[3])) + ((v1[0] * v1[0] + v1[1] * v1[1]) + (v1[2] * v1[2] + v1[3] * v1[3]));
;                     if (out) { *(f32x4*)(out + off) = v0; *(f32x4*)(out + off + 4) = v1; }
.LBB0_1333:
	v_lshl_add_u32 v146, s10, 8, v159
	v_lshl_or_b32 v144, s20, 8, v161
	v_ashrrev_i32_e32 v147, 31, v146
	v_ashrrev_i32_e32 v145, 31, v144
	v_lshlrev_b64 v[148:149], 10, v[146:147]
	v_lshl_add_u64 v[148:149], v[148:149], 0, v[144:145]
	v_lshl_add_u64 v[150:151], v[148:149], 2, s[36:37]
	v_lshlrev_b32_e32 v224, 2, v148
	global_load_dwordx4 v[192:195], v224, s[36:37]
	global_load_dwordx4 v[196:199], v224, s[36:37] offset:16
	global_load_dwordx4 v[200:203], v224, s[36:37] offset:512
	global_load_dwordx4 v[204:207], v224, s[36:37] offset:528
	v_add_u32_e32 v225, 0x10000, v224
	global_load_dwordx4 v[208:211], v225, s[36:37]
	global_load_dwordx4 v[212:215], v225, s[36:37] offset:16
	global_load_dwordx4 v[216:219], v225, s[36:37] offset:512
	global_load_dwordx4 v[220:223], v225, s[36:37] offset:528
	s_waitcnt vmcnt(4)
	v_cndmask_b32_e64 v152, 0, 1, s[50:51]
	v_cmp_ne_u32_e64 s[10:11], 1, v152
	s_andn2_b64 vcc, exec, s[50:51]
	v_lshl_add_u64 v[152:153], v[148:149], 2, s[42:43]
	v_pk_add_f32 v[126:127], v[126:127], v[194:195]
	v_pk_add_f32 v[124:125], v[124:125], v[192:193]
	v_pk_add_f32 v[122:123], v[122:123], v[198:199]
	v_pk_add_f32 v[120:121], v[120:121], v[196:197]
	s_cbranch_vccnz .LBB0_1335
	global_store_dwordx4 v[152:153], v[124:127], off
	global_store_dwordx4 v[152:153], v[120:123], off offset:16

; __device__ __forceinline__ v4u pack8(f32x4 a, f32x4 b) { v4u r; r.x = cvt_pk_bf16(a[0], a[1]); r.y = cvt_pk_bf16(a[2], a[3]); r.z = cvt_pk_bf16(b[0], b[1]); r.w = cvt_pk_bf16(b[2], b[3]); return r; }
;     __device__ __forceinline__ void operator()(const f32x4 (&acc)[2][2][4][2], const Unit& u, int wr, int wc, int fr, int fq) const {
;     ...
;                 for (int bj = 0; bj < 2; ++bj) {
;                     const size_t off = (size_t)row * 1024 + col0 + bj * 128;
;                     const f32x4 v0 = *(const f32x4*)(base + off) + acc[ai][bj][m][0], v1 = *(const f32x4*)(base + off + 4) + acc[ai][bj][m][1];
;                     s_ += ((v0[0] * v0[0] + v0[1] * v0[1]) + (v0[2] * v0[2] + v0[3] * v0[3])) + ((v1[0] * v1[0] + v1[1] * v1[1]) + (v1[2] * v1[2] + v1[3] * v1[3]));
;                     if (out) { *(f32x4*)(out + off) = v0; *(f32x4*)(out + off + 4) = v1; }
;                     if (outb) *(v4u*)(outb + off) = pack8(v0, v1);
.LBB0_1337:
	s_and_b64 vcc, exec, s[10:11]
	v_pk_add_f32 v[118:119], v[118:119], v[202:203]
	v_pk_add_f32 v[116:117], v[116:117], v[200:201]
	v_pk_add_f32 v[114:115], v[114:115], v[206:207]
	v_pk_add_f32 v[112:113], v[112:113], v[204:205]
	s_cbranch_vccnz .LBB0_1339
	global_store_dwordx4 v[152:153], v[116:119], off offset:512
	global_store_dwordx4 v[152:153], v[112:115], off offset:528

; __device__ __forceinline__ v4u pack8(f32x4 a, f32x4 b) { v4u r; r.x = cvt_pk_bf16(a[0], a[1]); r.y = cvt_pk_bf16(a[2], a[3]); r.z = cvt_pk_bf16(b[0], b[1]); r.w = cvt_pk_bf16(b[2], b[3]); return r; }
;     __device__ __forceinline__ void operator()(const f32x4 (&acc)[2][2][4][2], const Unit& u, int wr, int wc, int fr, int fq) const {
;     ...
;                 for (int bj = 0; bj < 2; ++bj) {
;                     const size_t off = (size_t)row * 1024 + col0 + bj * 128;
;                     const f32x4 v0 = *(const f32x4*)(base + off) + acc[ai][bj][m][0], v1 = *(const f32x4*)(base + off + 4) + acc[ai][bj][m][1];
;                     s_ += ((v0[0] * v0[0] + v0[1] * v0[1]) + (v0[2] * v0[2] + v0[3] * v0[3])) + ((v1[0] * v1[0] + v1[1] * v1[1]) + (v1[2] * v1[2] + v1[3] * v1[3]));
;                     if (out) { *(f32x4*)(out + off) = v0; *(f32x4*)(out + off + 4) = v1; }
;                     if (outb) *(v4u*)(outb + off) = pack8(v0, v1);
.LBB0_1343:
	s_or_b64 exec, exec, s[64:65]
	v_or_b32_e32 v112, 16, v146
	s_waitcnt lgkmcnt(0)
	v_ashrrev_i32_e32 v113, 31, v112
	v_lshlrev_b64 v[114:115], 10, v[112:113]
	v_lshl_add_u64 v[114:115], v[114:115], 0, v[144:145]
	v_lshl_add_u64 v[118:119], v[114:115], 2, s[36:37]
	v_add_u32_e32 v225, 0x20000, v224
	global_load_dwordx4 v[192:195], v225, s[36:37]
	global_load_dwordx4 v[196:199], v225, s[36:37] offset:16
	global_load_dwordx4 v[200:203], v225, s[36:37] offset:512
	global_load_dwordx4 v[204:207], v225, s[36:37] offset:528
	s_waitcnt vmcnt(4)
	s_and_b64 vcc, exec, s[10:11]
	v_lshl_add_u64 v[116:117], v[114:115], 2, s[42:43]
	v_pk_add_f32 v[110:111], v[110:111], v[210:211]
	v_pk_add_f32 v[108:109], v[108:109], v[208:209]
	v_pk_add_f32 v[106:107], v[106:107], v[214:215]
	v_pk_add_f32 v[104:105], v[104:105], v[212:213]
	s_cbranch_vccnz .LBB0_1345
	global_store_dwordx4 v[116:117], v[108:111], off
	global_store_dwordx4 v[116:117], v[104:107], off offset:16

; __device__ __forceinline__ v4u pack8(f32x4 a, f32x4 b) { v4u r; r.x = cvt_pk_bf16(a[0], a[1]); r.y = cvt_pk_bf16(a[2], a[3]); r.z = cvt_pk_bf16(b[0], b[1]); r.w = cvt_pk_bf16(b[2], b[3]); return r; }
;     __device__ __forceinline__ void operator()(const f32x4 (&acc)[2][2][4][2], const Unit& u, int wr, int wc, int fr, int fq) const {
;     ...
;                 for (int bj = 0; bj < 2; ++bj) {
;                     const size_t off = (size_t)row * 1024 + col0 + bj * 128;
;                     const f32x4 v0 = *(const f32x4*)(base + off) + acc[ai][bj][m][0], v1 = *(const f32x4*)(base + off + 4) + acc[ai][bj][m][1];
;                     s_ += ((v0[0] * v0[0] + v0[1] * v0[1]) + (v0[2] * v0[2] + v0[3] * v0[3])) + ((v1[0] * v1[0] + v1[1] * v1[1]) + (v1[2] * v1[2] + v1[3] * v1[3]));
;                     if (out) { *(f32x4*)(out + off) = v0; *(f32x4*)(out + off + 4) = v1; }
;                     if (outb) *(v4u*)(outb + off) = pack8(v0, v1);
.LBB0_1347:
	s_and_b64 vcc, exec, s[10:11]
	v_pk_add_f32 v[102:103], v[102:103], v[218:219]
	v_pk_add_f32 v[100:101], v[100:101], v[216:217]
	v_pk_add_f32 v[98:99], v[98:99], v[222:223]
	v_pk_add_f32 v[96:97], v[96:97], v[220:221]
	s_cbranch_vccnz .LBB0_1349
	global_store_dwordx4 v[116:117], v[100:103], off offset:512
	global_store_dwordx4 v[116:117], v[96:99], off offset:528

; __device__ __forceinline__ v4u pack8(f32x4 a, f32x4 b) { v4u r; r.x = cvt_pk_bf16(a[0], a[1]); r.y = cvt_pk_bf16(a[2], a[3]); r.z = cvt_pk_bf16(b[0], b[1]); r.w = cvt_pk_bf16(b[2], b[3]); return r; }
;     __device__ __forceinline__ void operator()(const f32x4 (&acc)[2][2][4][2], const Unit& u, int wr, int wc, int fr, int fq) const {
;     ...
;                 for (int bj = 0; bj < 2; ++bj) {
;                     const size_t off = (size_t)row * 1024 + col0 + bj * 128;
;                     const f32x4 v0 = *(const f32x4*)(base + off) + acc[ai][bj][m][0], v1 = *(const f32x4*)(base + off + 4) + acc[ai][bj][m][1];
;                     s_ += ((v0[0] * v0[0] + v0[1] * v0[1]) + (v0[2] * v0[2] + v0[3] * v0[3])) + ((v1[0] * v1[0] + v1[1] * v1[1]) + (v1[2] * v1[2] + v1[3] * v1[3]));
;                     if (out) { *(f32x4*)(out + off) = v0; *(f32x4*)(out + off + 4) = v1; }
;                     if (outb) *(v4u*)(outb + off) = pack8(v0, v1);
.LBB0_1353:
	s_or_b64 exec, exec, s[64:65]
	v_or_b32_e32 v96, 32, v146
	s_waitcnt lgkmcnt(0)
	v_ashrrev_i32_e32 v97, 31, v96
	v_lshlrev_b64 v[98:99], 10, v[96:97]
	v_lshl_add_u64 v[98:99], v[98:99], 0, v[144:145]
	v_lshl_add_u64 v[102:103], v[98:99], 2, s[36:37]
	v_add_u32_e32 v225, 0x30000, v224
	global_load_dwordx4 v[208:211], v225, s[36:37]
	global_load_dwordx4 v[212:215], v225, s[36:37] offset:16
	global_load_dwordx4 v[216:219], v225, s[36:37] offset:512
	global_load_dwordx4 v[220:223], v225, s[36:37] offset:528
	s_waitcnt vmcnt(4)
	s_and_b64 vcc, exec, s[10:11]
	v_lshl_add_u64 v[100:101], v[98:99], 2, s[42:43]
	v_pk_add_f32 v[94:95], v[94:95], v[194:195]
	v_pk_add_f32 v[92:93], v[92:93], v[192:193]
	v_pk_add_f32 v[90:91], v[90:91], v[198:199]
	v_pk_add_f32 v[88:89], v[88:89], v[196:197]
	s_cbranch_vccnz .LBB0_1355
	global_store_dwordx4 v[100:101], v[92:95], off
	global_store_dwordx4 v[100:101], v[88:91], off offset:16

; __device__ __forceinline__ v4u pack8(f32x4 a, f32x4 b) { v4u r; r.x = cvt_pk_bf16(a[0], a[1]); r.y = cvt_pk_bf16(a[2], a[3]); r.z = cvt_pk_bf16(b[0], b[1]); r.w = cvt_pk_bf16(b[2], b[3]); return r; }
;     __device__ __forceinline__ void operator()(const f32x4 (&acc)[2][2][4][2], const Unit& u, int wr, int wc, int fr, int fq) const {
;     ...
;                 for (int bj = 0; bj < 2; ++bj) {
;                     const size_t off = (size_t)row * 1024 + col0 + bj * 128;
;                     const f32x4 v0 = *(const f32x4*)(base + off) + acc[ai][bj][m][0], v1 = *(const f32x4*)(base + off + 4) + acc[ai][bj][m][1];
;                     s_ += ((v0[0] * v0[0] + v0[1] * v0[1]) + (v0[2] * v0[2] + v0[3] * v0[3])) + ((v1[0] * v1[0] + v1[1] * v1[1]) + (v1[2] * v1[2] + v1[3] * v1[3]));
;                     if (out) { *(f32x4*)(out + off) = v0; *(f32x4*)(out + off + 4) = v1; }
;                     if (outb) *(v4u*)(outb + off) = pack8(v0, v1);
.LBB0_1357:
	s_and_b64 vcc, exec, s[10:11]
	v_pk_add_f32 v[86:87], v[86:87], v[202:203]
	v_pk_add_f32 v[84:85], v[84:85], v[200:201]
	v_pk_add_f32 v[82:83], v[82:83], v[206:207]
	v_pk_add_f32 v[80:81], v[80:81], v[204:205]
	s_cbranch_vccnz .LBB0_1359
	global_store_dwordx4 v[100:101], v[84:87], off offset:512
	global_store_dwordx4 v[100:101], v[80:83], off offset:528

; __device__ __forceinline__ v4u pack8(f32x4 a, f32x4 b) { v4u r; r.x = cvt_pk_bf16(a[0], a[1]); r.y = cvt_pk_bf16(a[2], a[3]); r.z = cvt_pk_bf16(b[0], b[1]); r.w = cvt_pk_bf16(b[2], b[3]); return r; }
;     __device__ __forceinline__ void operator()(const f32x4 (&acc)[2][2][4][2], const Unit& u, int wr, int wc, int fr, int fq) const {
;     ...
;                 for (int bj = 0; bj < 2; ++bj) {
;                     const size_t off = (size_t)row * 1024 + col0 + bj * 128;
;                     const f32x4 v0 = *(const f32x4*)(base + off) + acc[ai][bj][m][0], v1 = *(const f32x4*)(base + off + 4) + acc[ai][bj][m][1];
;                     s_ += ((v0[0] * v0[0] + v0[1] * v0[1]) + (v0[2] * v0[2] + v0[3] * v0[3])) + ((v1[0] * v1[0] + v1[1] * v1[1]) + (v1[2] * v1[2] + v1[3] * v1[3]));
;                     if (out) { *(f32x4*)(out + off) = v0; *(f32x4*)(out + off + 4) = v1; }
;                     if (outb) *(v4u*)(outb + off) = pack8(v0, v1);
.LBB0_1363:
	s_or_b64 exec, exec, s[64:65]
	v_or_b32_e32 v80, 48, v146
	s_waitcnt lgkmcnt(0)
	v_ashrrev_i32_e32 v81, 31, v80
	v_lshlrev_b64 v[82:83], 10, v[80:81]
	v_lshl_add_u64 v[82:83], v[82:83], 0, v[144:145]
	v_lshl_add_u64 v[86:87], v[82:83], 2, s[36:37]
	v_add_u32_e32 v225, 0x80000, v224
	global_load_dwordx4 v[192:195], v225, s[36:37]
	global_load_dwordx4 v[196:199], v225, s[36:37] offset:16
	global_load_dwordx4 v[200:203], v225, s[36:37] offset:512
	global_load_dwordx4 v[204:207], v225, s[36:37] offset:528
	s_waitcnt vmcnt(4)
	s_and_b64 vcc, exec, s[10:11]
	v_lshl_add_u64 v[84:85], v[82:83], 2, s[42:43]
	v_pk_add_f32 v[78:79], v[78:79], v[210:211]
	v_pk_add_f32 v[76:77], v[76:77], v[208:209]
	v_pk_add_f32 v[74:75], v[74:75], v[214:215]
	v_pk_add_f32 v[72:73], v[72:73], v[212:213]
	s_cbranch_vccnz .LBB0_1365
	global_store_dwordx4 v[84:85], v[76:79], off
	global_store_dwordx4 v[84:85], v[72:75], off offset:16

; __device__ __forceinline__ v4u pack8(f32x4 a, f32x4 b) { v4u r; r.x = cvt_pk_bf16(a[0], a[1]); r.y = cvt_pk_bf16(a[2], a[3]); r.z = cvt_pk_bf16(b[0], b[1]); r.w = cvt_pk_bf16(b[2], b[3]); return r; }
;     __device__ __forceinline__ void operator()(const f32x4 (&acc)[2][2][4][2], const Unit& u, int wr, int wc, int fr, int fq) const {
;     ...
;                 for (int bj = 0; bj < 2; ++bj) {
;                     const size_t off = (size_t)row * 1024 + col0 + bj * 128;
;                     const f32x4 v0 = *(const f32x4*)(base + off) + acc[ai][bj][m][0], v1 = *(const f32x4*)(base + off + 4) + acc[ai][bj][m][1];
;                     s_ += ((v0[0] * v0[0] + v0[1] * v0[1]) + (v0[2] * v0[2] + v0[3] * v0[3])) + ((v1[0] * v1[0] + v1[1] * v1[1]) + (v1[2] * v1[2] + v1[3] * v1[3]));
;                     if (out) { *(f32x4*)(out + off) = v0; *(f32x4*)(out + off + 4) = v1; }
;                     if (outb) *(v4u*)(outb + off) = pack8(v0, v1);
.LBB0_1367:
	s_and_b64 vcc, exec, s[10:11]
	v_pk_add_f32 v[70:71], v[70:71], v[218:219]
	v_pk_add_f32 v[68:69], v[68:69], v[216:217]
	v_pk_add_f32 v[66:67], v[66:67], v[222:223]
	v_pk_add_f32 v[64:65], v[64:65], v[220:221]
	s_cbranch_vccnz .LBB0_1369
	global_store_dwordx4 v[84:85], v[68:71], off offset:512
	global_store_dwordx4 v[84:85], v[64:67], off offset:528

; __device__ __forceinline__ v4u pack8(f32x4 a, f32x4 b) { v4u r; r.x = cvt_pk_bf16(a[0], a[1]); r.y = cvt_pk_bf16(a[2], a[3]); r.z = cvt_pk_bf16(b[0], b[1]); r.w = cvt_pk_bf16(b[2], b[3]); return r; }
;     __device__ __forceinline__ void operator()(const f32x4 (&acc)[2][2][4][2], const Unit& u, int wr, int wc, int fr, int fq) const {
;     ...
;                 for (int bj = 0; bj < 2; ++bj) {
;                     const size_t off = (size_t)row * 1024 + col0 + bj * 128;
;                     const f32x4 v0 = *(const f32x4*)(base + off) + acc[ai][bj][m][0], v1 = *(const f32x4*)(base + off + 4) + acc[ai][bj][m][1];
;                     s_ += ((v0[0] * v0[0] + v0[1] * v0[1]) + (v0[2] * v0[2] + v0[3] * v0[3])) + ((v1[0] * v1[0] + v1[1] * v1[1]) + (v1[2] * v1[2] + v1[3] * v1[3]));
;                     if (out) { *(f32x4*)(out + off) = v0; *(f32x4*)(out + off + 4) = v1; }
;                     if (outb) *(v4u*)(outb + off) = pack8(v0, v1);
.LBB0_1373:
	s_or_b64 exec, exec, s[64:65]
	v_add_u32_e32 v64, 0x80, v146
	s_waitcnt lgkmcnt(0)
	v_ashrrev_i32_e32 v65, 31, v64
	v_lshlrev_b64 v[66:67], 10, v[64:65]
	v_lshl_add_u64 v[66:67], v[66:67], 0, v[144:145]
	v_lshl_add_u64 v[70:71], v[66:67], 2, s[36:37]
	v_add_u32_e32 v225, 0x90000, v224
	global_load_dwordx4 v[208:211], v225, s[36:37]
	global_load_dwordx4 v[212:215], v225, s[36:37] offset:16
	global_load_dwordx4 v[216:219], v225, s[36:37] offset:512
	global_load_dwordx4 v[220:223], v225, s[36:37] offset:528
	s_waitcnt vmcnt(4)
	s_and_b64 vcc, exec, s[10:11]
	v_lshl_add_u64 v[68:69], v[66:67], 2, s[42:43]
	v_pk_add_f32 v[62:63], v[62:63], v[194:195]
	v_pk_add_f32 v[60:61], v[60:61], v[192:193]
	v_pk_add_f32 v[58:59], v[58:59], v[198:199]
	v_pk_add_f32 v[56:57], v[56:57], v[196:197]
	s_cbranch_vccnz .LBB0_1375
	global_store_dwordx4 v[68:69], v[60:63], off
	global_store_dwordx4 v[68:69], v[56:59], off offset:16

; __device__ __forceinline__ v4u pack8(f32x4 a, f32x4 b) { v4u r; r.x = cvt_pk_bf16(a[0], a[1]); r.y = cvt_pk_bf16(a[2], a[3]); r.z = cvt_pk_bf16(b[0], b[1]); r.w = cvt_pk_bf16(b[2], b[3]); return r; }
;     __device__ __forceinline__ void operator()(const f32x4 (&acc)[2][2][4][2], const Unit& u, int wr, int wc, int fr, int fq) const {
;     ...
;                 for (int bj = 0; bj < 2; ++bj) {
;                     const size_t off = (size_t)row * 1024 + col0 + bj * 128;
;                     const f32x4 v0 = *(const f32x4*)(base + off) + acc[ai][bj][m][0], v1 = *(const f32x4*)(base + off + 4) + acc[ai][bj][m][1];
;                     s_ += ((v0[0] * v0[0] + v0[1] * v0[1]) + (v0[2] * v0[2] + v0[3] * v0[3])) + ((v1[0] * v1[0] + v1[1] * v1[1]) + (v1[2] * v1[2] + v1[3] * v1[3]));
;                     if (out) { *(f32x4*)(out + off) = v0; *(f32x4*)(out + off + 4) = v1; }
;                     if (outb) *(v4u*)(outb + off) = pack8(v0, v1);
.LBB0_1377:
	s_and_b64 vcc, exec, s[10:11]
	v_pk_add_f32 v[54:55], v[54:55], v[202:203]
	v_pk_add_f32 v[52:53], v[52:53], v[200:201]
	v_pk_add_f32 v[50:51], v[50:51], v[206:207]
	v_pk_add_f32 v[48:49], v[48:49], v[204:205]
	s_cbranch_vccnz .LBB0_1379
	global_store_dwordx4 v[68:69], v[52:55], off offset:512
	global_store_dwordx4 v[68:69], v[48:51], off offset:528

; __device__ __forceinline__ v4u pack8(f32x4 a, f32x4 b) { v4u r; r.x = cvt_pk_bf16(a[0], a[1]); r.y = cvt_pk_bf16(a[2], a[3]); r.z = cvt_pk_bf16(b[0], b[1]); r.w = cvt_pk_bf16(b[2], b[3]); return r; }
;     __device__ __forceinline__ void operator()(const f32x4 (&acc)[2][2][4][2], const Unit& u, int wr, int wc, int fr, int fq) const {
;     ...
;                 for (int bj = 0; bj < 2; ++bj) {
;                     const size_t off = (size_t)row * 1024 + col0 + bj * 128;
;                     const f32x4 v0 = *(const f32x4*)(base + off) + acc[ai][bj][m][0], v1 = *(const f32x4*)(base + off + 4) + acc[ai][bj][m][1];
;                     s_ += ((v0[0] * v0[0] + v0[1] * v0[1]) + (v0[2] * v0[2] + v0[3] * v0[3])) + ((v1[0] * v1[0] + v1[1] * v1[1]) + (v1[2] * v1[2] + v1[3] * v1[3]));
;                     if (out) { *(f32x4*)(out + off) = v0; *(f32x4*)(out + off + 4) = v1; }
;                     if (outb) *(v4u*)(outb + off) = pack8(v0, v1);
.LBB0_1383:
	s_or_b64 exec, exec, s[64:65]
	v_add_u32_e32 v48, 0x90, v146
	s_waitcnt lgkmcnt(0)
	v_ashrrev_i32_e32 v49, 31, v48
	v_lshlrev_b64 v[50:51], 10, v[48:49]
	v_lshl_add_u64 v[50:51], v[50:51], 0, v[144:145]
	v_lshl_add_u64 v[54:55], v[50:51], 2, s[36:37]
	v_add_u32_e32 v225, 0xa0000, v224
	global_load_dwordx4 v[192:195], v225, s[36:37]
	global_load_dwordx4 v[196:199], v225, s[36:37] offset:16
	global_load_dwordx4 v[200:203], v225, s[36:37] offset:512
	global_load_dwordx4 v[204:207], v225, s[36:37] offset:528
	s_waitcnt vmcnt(4)
	s_and_b64 vcc, exec, s[10:11]
	v_lshl_add_u64 v[52:53], v[50:51], 2, s[42:43]
	v_pk_add_f32 v[46:47], v[46:47], v[210:211]
	v_pk_add_f32 v[44:45], v[44:45], v[208:209]
	v_pk_add_f32 v[42:43], v[42:43], v[214:215]
	v_pk_add_f32 v[40:41], v[40:41], v[212:213]
	s_cbranch_vccnz .LBB0_1385
	global_store_dwordx4 v[52:53], v[44:47], off
	global_store_dwordx4 v[52:53], v[40:43], off offset:16

; __device__ __forceinline__ v4u pack8(f32x4 a, f32x4 b) { v4u r; r.x = cvt_pk_bf16(a[0], a[1]); r.y = cvt_pk_bf16(a[2], a[3]); r.z = cvt_pk_bf16(b[0], b[1]); r.w = cvt_pk_bf16(b[2], b[3]); return r; }
;     __device__ __forceinline__ void operator()(const f32x4 (&acc)[2][2][4][2], const Unit& u, int wr, int wc, int fr, int fq) const {
;     ...
;                 for (int bj = 0; bj < 2; ++bj) {
;                     const size_t off = (size_t)row * 1024 + col0 + bj * 128;
;                     const f32x4 v0 = *(const f32x4*)(base + off) + acc[ai][bj][m][0], v1 = *(const f32x4*)(base + off + 4) + acc[ai][bj][m][1];
;                     s_ += ((v0[0] * v0[0] + v0[1] * v0[1]) + (v0[2] * v0[2] + v0[3] * v0[3])) + ((v1[0] * v1[0] + v1[1] * v1[1]) + (v1[2] * v1[2] + v1[3] * v1[3]));
;                     if (out) { *(f32x4*)(out + off) = v0; *(f32x4*)(out + off + 4) = v1; }
;                     if (outb) *(v4u*)(outb + off) = pack8(v0, v1);
.LBB0_1387:
	s_and_b64 vcc, exec, s[10:11]
	v_pk_add_f32 v[38:39], v[38:39], v[218:219]
	v_pk_add_f32 v[36:37], v[36:37], v[216:217]
	v_pk_add_f32 v[34:35], v[34:35], v[222:223]
	v_pk_add_f32 v[32:33], v[32:33], v[220:221]
	s_cbranch_vccnz .LBB0_1389
	global_store_dwordx4 v[52:53], v[36:39], off offset:512
	global_store_dwordx4 v[52:53], v[32:35], off offset:528

; __device__ __forceinline__ v4u pack8(f32x4 a, f32x4 b) { v4u r; r.x = cvt_pk_bf16(a[0], a[1]); r.y = cvt_pk_bf16(a[2], a[3]); r.z = cvt_pk_bf16(b[0], b[1]); r.w = cvt_pk_bf16(b[2], b[3]); return r; }
;     __device__ __forceinline__ void operator()(const f32x4 (&acc)[2][2][4][2], const Unit& u, int wr, int wc, int fr, int fq) const {
;     ...
;                 for (int bj = 0; bj < 2; ++bj) {
;                     const size_t off = (size_t)row * 1024 + col0 + bj * 128;
;                     const f32x4 v0 = *(const f32x4*)(base + off) + acc[ai][bj][m][0], v1 = *(const f32x4*)(base + off + 4) + acc[ai][bj][m][1];
;                     s_ += ((v0[0] * v0[0] + v0[1] * v0[1]) + (v0[2] * v0[2] + v0[3] * v0[3])) + ((v1[0] * v1[0] + v1[1] * v1[1]) + (v1[2] * v1[2] + v1[3] * v1[3]));
;                     if (out) { *(f32x4*)(out + off) = v0; *(f32x4*)(out + off + 4) = v1; }
;                     if (outb) *(v4u*)(outb + off) = pack8(v0, v1);
.LBB0_1393:
	s_or_b64 exec, exec, s[64:65]
	v_add_u32_e32 v32, 0xa0, v146
	s_waitcnt lgkmcnt(0)
	v_ashrrev_i32_e32 v33, 31, v32
	v_lshlrev_b64 v[34:35], 10, v[32:33]
	v_lshl_add_u64 v[34:35], v[34:35], 0, v[144:145]
	v_lshl_add_u64 v[38:39], v[34:35], 2, s[36:37]
	v_add_u32_e32 v225, 0xb0000, v224
	global_load_dwordx4 v[208:211], v225, s[36:37]
	global_load_dwordx4 v[212:215], v225, s[36:37] offset:16
	global_load_dwordx4 v[216:219], v225, s[36:37] offset:512
	global_load_dwordx4 v[220:223], v225, s[36:37] offset:528
	s_waitcnt vmcnt(4)
	s_and_b64 vcc, exec, s[10:11]
	v_lshl_add_u64 v[36:37], v[34:35], 2, s[42:43]
	v_pk_add_f32 v[30:31], v[30:31], v[194:195]
	v_pk_add_f32 v[28:29], v[28:29], v[192:193]
	v_pk_add_f32 v[26:27], v[26:27], v[198:199]
	v_pk_add_f32 v[24:25], v[24:25], v[196:197]
	s_cbranch_vccnz .LBB0_1395
	global_store_dwordx4 v[36:37], v[28:31], off
	global_store_dwordx4 v[36:37], v[24:27], off offset:16

; __device__ __forceinline__ v4u pack8(f32x4 a, f32x4 b) { v4u r; r.x = cvt_pk_bf16(a[0], a[1]); r.y = cvt_pk_bf16(a[2], a[3]); r.z = cvt_pk_bf16(b[0], b[1]); r.w = cvt_pk_bf16(b[2], b[3]); return r; }
;     __device__ __forceinline__ void operator()(const f32x4 (&acc)[2][2][4][2], const Unit& u, int wr, int wc, int fr, int fq) const {
;     ...
;                 for (int bj = 0; bj < 2; ++bj) {
;                     const size_t off = (size_t)row * 1024 + col0 + bj * 128;
;                     const f32x4 v0 = *(const f32x4*)(base + off) + acc[ai][bj][m][0], v1 = *(const f32x4*)(base + off + 4) + acc[ai][bj][m][1];
;                     s_ += ((v0[0] * v0[0] + v0[1] * v0[1]) + (v0[2] * v0[2] + v0[3] * v0[3])) + ((v1[0] * v1[0] + v1[1] * v1[1]) + (v1[2] * v1[2] + v1[3] * v1[3]));
;                     if (out) { *(f32x4*)(out + off) = v0; *(f32x4*)(out + off + 4) = v1; }
;                     if (outb) *(v4u*)(outb + off) = pack8(v0, v1);
.LBB0_1397:
	s_and_b64 vcc, exec, s[10:11]
	v_pk_add_f32 v[22:23], v[22:23], v[202:203]
	v_pk_add_f32 v[20:21], v[20:21], v[200:201]
	v_pk_add_f32 v[18:19], v[18:19], v[206:207]
	v_pk_add_f32 v[16:17], v[16:17], v[204:205]
	s_cbranch_vccnz .LBB0_1399
	global_store_dwordx4 v[36:37], v[20:23], off offset:512
	global_store_dwordx4 v[36:37], v[16:19], off offset:528

; __device__ __forceinline__ v4u pack8(f32x4 a, f32x4 b) { v4u r; r.x = cvt_pk_bf16(a[0], a[1]); r.y = cvt_pk_bf16(a[2], a[3]); r.z = cvt_pk_bf16(b[0], b[1]); r.w = cvt_pk_bf16(b[2], b[3]); return r; }
;     __device__ __forceinline__ void operator()(const f32x4 (&acc)[2][2][4][2], const Unit& u, int wr, int wc, int fr, int fq) const {
;     ...
;                 for (int bj = 0; bj < 2; ++bj) {
;                     const size_t off = (size_t)row * 1024 + col0 + bj * 128;
;                     const f32x4 v0 = *(const f32x4*)(base + off) + acc[ai][bj][m][0], v1 = *(const f32x4*)(base + off + 4) + acc[ai][bj][m][1];
;                     s_ += ((v0[0] * v0[0] + v0[1] * v0[1]) + (v0[2] * v0[2] + v0[3] * v0[3])) + ((v1[0] * v1[0] + v1[1] * v1[1]) + (v1[2] * v1[2] + v1[3] * v1[3]));
;                     if (out) { *(f32x4*)(out + off) = v0; *(f32x4*)(out + off + 4) = v1; }
;                     if (outb) *(v4u*)(outb + off) = pack8(v0, v1);
.LBB0_1403:
	s_or_b64 exec, exec, s[64:65]
	v_add_u32_e32 v16, 0xb0, v146
	s_waitcnt lgkmcnt(0)
	v_ashrrev_i32_e32 v17, 31, v16
	v_lshlrev_b64 v[18:19], 10, v[16:17]
	v_lshl_add_u64 v[18:19], v[18:19], 0, v[144:145]
	v_lshl_add_u64 v[22:23], v[18:19], 2, s[36:37]
	s_waitcnt vmcnt(0)
	s_and_b64 vcc, exec, s[10:11]
	v_lshl_add_u64 v[20:21], v[18:19], 2, s[42:43]
	v_pk_add_f32 v[14:15], v[14:15], v[210:211]
	v_pk_add_f32 v[12:13], v[12:13], v[208:209]
	v_pk_add_f32 v[10:11], v[10:11], v[214:215]
	v_pk_add_f32 v[8:9], v[8:9], v[212:213]
	s_cbranch_vccnz .LBB0_1405
	global_store_dwordx4 v[20:21], v[12:15], off
	global_store_dwordx4 v[20:21], v[8:11], off offset:16

; __device__ __forceinline__ v4u pack8(f32x4 a, f32x4 b) { v4u r; r.x = cvt_pk_bf16(a[0], a[1]); r.y = cvt_pk_bf16(a[2], a[3]); r.z = cvt_pk_bf16(b[0], b[1]); r.w = cvt_pk_bf16(b[2], b[3]); return r; }
;     __device__ __forceinline__ void operator()(const f32x4 (&acc)[2][2][4][2], const Unit& u, int wr, int wc, int fr, int fq) const {
;     ...
;                 for (int bj = 0; bj < 2; ++bj) {
;                     const size_t off = (size_t)row * 1024 + col0 + bj * 128;
;                     const f32x4 v0 = *(const f32x4*)(base + off) + acc[ai][bj][m][0], v1 = *(const f32x4*)(base + off + 4) + acc[ai][bj][m][1];
;                     s_ += ((v0[0] * v0[0] + v0[1] * v0[1]) + (v0[2] * v0[2] + v0[3] * v0[3])) + ((v1[0] * v1[0] + v1[1] * v1[1]) + (v1[2] * v1[2] + v1[3] * v1[3]));
;                     if (out) { *(f32x4*)(out + off) = v0; *(f32x4*)(out + off + 4) = v1; }
;                     if (outb) *(v4u*)(outb + off) = pack8(v0, v1);
.LBB0_1407:
	s_and_b64 vcc, exec, s[10:11]
	v_pk_add_f32 v[6:7], v[6:7], v[218:219]
	v_pk_add_f32 v[4:5], v[4:5], v[216:217]
	v_pk_add_f32 v[2:3], v[2:3], v[222:223]
	v_pk_add_f32 v[0:1], v[0:1], v[220:221]
	s_cbranch_vccnz .LBB0_1409
	global_store_dwordx4 v[20:21], v[4:7], off offset:512
	global_store_dwordx4 v[20:21], v[0:3], off offset:528
